# scan_unit half-WG stagger + pipelined grp1 attention sub-loop
# speedup vs baseline: 1.0612x; 1.0170x over previous
.LBB0_506:
	v_add_u32_e32 v173, 0x2000, v129
	ds_read_b128 v[2:5], v164
	ds_read_b128 v[6:9], v164 offset:32
	s_waitcnt lgkmcnt(0)
	v_mfma_f32_32x32x16_bf16 v[80:95], v[2:5], v[96:99], 0
	v_mfma_f32_32x32x16_bf16 v[80:95], v[6:9], v[100:103], v[80:95]
	ds_read_b128 v[2:5], v164 offset:2560
	ds_read_b128 v[6:9], v164 offset:2592
	ds_read2_b64 v[232:235], v129 offset0:0 offset1:2
	ds_read2_b64 v[236:239], v129 offset0:4 offset1:6
	ds_read2_b64 v[244:247], v173 offset0:32 offset1:34
	ds_read2_b64 v[214:217], v173 offset0:36 offset1:38
	s_waitcnt lgkmcnt(4)
	v_mfma_f32_32x32x16_bf16 v[178:193], v[2:5], v[96:99], 0
	v_mfma_f32_32x32x16_bf16 v[178:193], v[6:9], v[100:103], v[178:193]
	s_nop 7
	v_max3_f32 v248, v80, v81, v82
	v_max3_f32 v249, v83, v84, v85
	v_max3_f32 v218, v86, v87, v88
	v_max3_f32 v219, v89, v90, v91
	v_max3_f32 v220, v92, v93, v94
	v_max3_f32 v248, v248, v249, v218
	v_max3_f32 v219, v219, v220, v95
	v_max_f32_e32 v248, v248, v219
	v_mov_b32_e32 v249, v248
	s_nop 1
	v_permlane32_swap_b32_e32 v248, v249
	v_max_f32_e32 v248, v248, v249
	v_mul_f32_e32 v248, 0x3e8293ee, v248
	v_max_f32_e32 v218, v133, v248
	v_sub_f32_e32 v0, v133, v218
	v_exp_f32_e32 v0, v0
	v_mov_b32_e32 v133, v218
	v_cmp_neq_f32_e32 vcc, 1.0, v0
	s_cmp_lg_u64 vcc, 0
	s_cbranch_scc0 .Lattn1_norescale_0
	v_pk_mul_f32 v[48:49], v[48:49], v[0:1] op_sel_hi:[1,0]
	v_pk_mul_f32 v[50:51], v[50:51], v[0:1] op_sel_hi:[1,0]
	v_pk_mul_f32 v[52:53], v[52:53], v[0:1] op_sel_hi:[1,0]
	v_pk_mul_f32 v[54:55], v[54:55], v[0:1] op_sel_hi:[1,0]
	v_pk_mul_f32 v[56:57], v[56:57], v[0:1] op_sel_hi:[1,0]
	v_pk_mul_f32 v[58:59], v[58:59], v[0:1] op_sel_hi:[1,0]
	v_pk_mul_f32 v[60:61], v[60:61], v[0:1] op_sel_hi:[1,0]
	v_pk_mul_f32 v[62:63], v[62:63], v[0:1] op_sel_hi:[1,0]
	v_pk_mul_f32 v[64:65], v[64:65], v[0:1] op_sel_hi:[1,0]
	v_pk_mul_f32 v[66:67], v[66:67], v[0:1] op_sel_hi:[1,0]
	v_pk_mul_f32 v[68:69], v[68:69], v[0:1] op_sel_hi:[1,0]
	v_pk_mul_f32 v[70:71], v[70:71], v[0:1] op_sel_hi:[1,0]
	v_pk_mul_f32 v[72:73], v[72:73], v[0:1] op_sel_hi:[1,0]
	v_pk_mul_f32 v[74:75], v[74:75], v[0:1] op_sel_hi:[1,0]
	v_pk_mul_f32 v[76:77], v[76:77], v[0:1] op_sel_hi:[1,0]
	v_pk_mul_f32 v[78:79], v[78:79], v[0:1] op_sel_hi:[1,0]
.Lattn1_norescale_0:
	v_fma_f32 v15, v80, s39, -v133
	v_exp_f32_e32 v80, v15
	v_fma_f32 v153, v81, s39, -v133
	v_exp_f32_e32 v81, v153
	v_fma_f32 v15, v82, s39, -v133
	v_exp_f32_e32 v82, v15
	v_fma_f32 v153, v83, s39, -v133
	v_exp_f32_e32 v83, v153
	v_fma_f32 v15, v84, s39, -v133
	v_exp_f32_e32 v84, v15
	v_fma_f32 v153, v85, s39, -v133
	v_exp_f32_e32 v85, v153
	v_fma_f32 v15, v86, s39, -v133
	v_exp_f32_e32 v86, v15
	v_fma_f32 v153, v87, s39, -v133
	v_exp_f32_e32 v87, v153
	v_fma_f32 v15, v88, s39, -v133
	v_exp_f32_e32 v88, v15
	v_fma_f32 v153, v89, s39, -v133
	v_exp_f32_e32 v89, v153
	v_fma_f32 v15, v90, s39, -v133
	v_exp_f32_e32 v90, v15
	v_fma_f32 v153, v91, s39, -v133
	v_exp_f32_e32 v91, v153
	v_fma_f32 v15, v92, s39, -v133
	v_exp_f32_e32 v92, v15
	v_fma_f32 v153, v93, s39, -v133
	v_exp_f32_e32 v93, v153
	v_fma_f32 v15, v94, s39, -v133
	v_exp_f32_e32 v94, v15
	v_fma_f32 v153, v95, s39, -v133
	v_exp_f32_e32 v95, v153
	v_cvt_pk_bf16_f32 v10, v80, v81
	v_cvt_pk_bf16_f32 v11, v82, v83
	v_cvt_pk_bf16_f32 v12, v84, v85
	v_cvt_pk_bf16_f32 v13, v86, v87
	v_cvt_pk_bf16_f32 v240, v88, v89
	v_cvt_pk_bf16_f32 v241, v90, v91
	v_cvt_pk_bf16_f32 v242, v92, v93
	v_cvt_pk_bf16_f32 v243, v94, v95
	s_waitcnt lgkmcnt(0)
	s_nop 0
	v_mfma_f32_32x32x16_bf16 v[48:63], v[232:235], v[10:13], v[48:63]
	v_add_f32_e32 v194, v80, v81
	v_add_f32_e32 v195, v82, v83
	v_add_f32_e32 v155, v84, v85
	v_add_f32_e32 v169, v86, v87
	v_add_f32_e32 v194, v88, v194
	v_mfma_f32_32x32x16_bf16 v[48:63], v[236:239], v[240:243], v[48:63]
	v_add_f32_e32 v195, v89, v195
	v_add_f32_e32 v155, v90, v155
	v_add_f32_e32 v169, v91, v169
	v_add_f32_e32 v194, v92, v194
	v_add_f32_e32 v195, v93, v195
	v_mfma_f32_32x32x16_bf16 v[64:79], v[244:247], v[10:13], v[64:79]
	v_add_f32_e32 v155, v94, v155
	v_add_f32_e32 v169, v95, v169
	v_add_f32_e32 v194, v194, v195
	v_add_f32_e32 v155, v155, v169
	v_add_f32_e32 v194, v194, v155
	v_mfma_f32_32x32x16_bf16 v[64:79], v[214:217], v[240:243], v[64:79]
	v_fmac_f32_e32 v194, v151, v0
	v_mov_b32_e32 v151, v194
	ds_read_b128 v[2:5], v164 offset:5120
	ds_read_b128 v[6:9], v164 offset:5152
	ds_read2_b64 v[232:235], v129 offset0:8 offset1:10
	ds_read2_b64 v[236:239], v129 offset0:12 offset1:14
	ds_read2_b64 v[244:247], v173 offset0:40 offset1:42
	ds_read2_b64 v[214:217], v173 offset0:44 offset1:46
	s_waitcnt lgkmcnt(4)
	v_mfma_f32_32x32x16_bf16 v[80:95], v[2:5], v[96:99], 0
	v_mfma_f32_32x32x16_bf16 v[80:95], v[6:9], v[100:103], v[80:95]
	v_max3_f32 v248, v178, v179, v180
	v_max3_f32 v249, v181, v182, v183
	v_max3_f32 v218, v184, v185, v186
	v_max3_f32 v219, v187, v188, v189
	v_max3_f32 v220, v190, v191, v192
	v_max3_f32 v248, v248, v249, v218
	v_max3_f32 v219, v219, v220, v193
	v_max_f32_e32 v248, v248, v219
	v_mov_b32_e32 v249, v248
	s_nop 1
	v_permlane32_swap_b32_e32 v248, v249
	v_max_f32_e32 v248, v248, v249
	v_mul_f32_e32 v248, 0x3e8293ee, v248
	v_max_f32_e32 v218, v133, v248
	v_sub_f32_e32 v0, v133, v218
	v_exp_f32_e32 v0, v0
	v_mov_b32_e32 v133, v218
	v_cmp_neq_f32_e32 vcc, 1.0, v0
	s_cmp_lg_u64 vcc, 0
	s_cbranch_scc0 .Lattn1_norescale_1
	v_pk_mul_f32 v[48:49], v[48:49], v[0:1] op_sel_hi:[1,0]
	v_pk_mul_f32 v[50:51], v[50:51], v[0:1] op_sel_hi:[1,0]
	v_pk_mul_f32 v[52:53], v[52:53], v[0:1] op_sel_hi:[1,0]
	v_pk_mul_f32 v[54:55], v[54:55], v[0:1] op_sel_hi:[1,0]
	v_pk_mul_f32 v[56:57], v[56:57], v[0:1] op_sel_hi:[1,0]
	v_pk_mul_f32 v[58:59], v[58:59], v[0:1] op_sel_hi:[1,0]
	v_pk_mul_f32 v[60:61], v[60:61], v[0:1] op_sel_hi:[1,0]
	v_pk_mul_f32 v[62:63], v[62:63], v[0:1] op_sel_hi:[1,0]
	v_pk_mul_f32 v[64:65], v[64:65], v[0:1] op_sel_hi:[1,0]
	v_pk_mul_f32 v[66:67], v[66:67], v[0:1] op_sel_hi:[1,0]
	v_pk_mul_f32 v[68:69], v[68:69], v[0:1] op_sel_hi:[1,0]
	v_pk_mul_f32 v[70:71], v[70:71], v[0:1] op_sel_hi:[1,0]
	v_pk_mul_f32 v[72:73], v[72:73], v[0:1] op_sel_hi:[1,0]
	v_pk_mul_f32 v[74:75], v[74:75], v[0:1] op_sel_hi:[1,0]
	v_pk_mul_f32 v[76:77], v[76:77], v[0:1] op_sel_hi:[1,0]
	v_pk_mul_f32 v[78:79], v[78:79], v[0:1] op_sel_hi:[1,0]
.Lattn1_norescale_1:
	v_fma_f32 v15, v178, s39, -v133
	v_exp_f32_e32 v178, v15
	v_fma_f32 v153, v179, s39, -v133
	v_exp_f32_e32 v179, v153
	v_fma_f32 v15, v180, s39, -v133
	v_exp_f32_e32 v180, v15
	v_fma_f32 v153, v181, s39, -v133
	v_exp_f32_e32 v181, v153
	v_fma_f32 v15, v182, s39, -v133
	v_exp_f32_e32 v182, v15
	v_fma_f32 v153, v183, s39, -v133
	v_exp_f32_e32 v183, v153
	v_fma_f32 v15, v184, s39, -v133
	v_exp_f32_e32 v184, v15
	v_fma_f32 v153, v185, s39, -v133
	v_exp_f32_e32 v185, v153
	v_fma_f32 v15, v186, s39, -v133
	v_exp_f32_e32 v186, v15
	v_fma_f32 v153, v187, s39, -v133
	v_exp_f32_e32 v187, v153
	v_fma_f32 v15, v188, s39, -v133
	v_exp_f32_e32 v188, v15
	v_fma_f32 v153, v189, s39, -v133
	v_exp_f32_e32 v189, v153
	v_fma_f32 v15, v190, s39, -v133
	v_exp_f32_e32 v190, v15
	v_fma_f32 v153, v191, s39, -v133
	v_exp_f32_e32 v191, v153
	v_fma_f32 v15, v192, s39, -v133
	v_exp_f32_e32 v192, v15
	v_fma_f32 v153, v193, s39, -v133
	v_exp_f32_e32 v193, v153
	v_cvt_pk_bf16_f32 v10, v178, v179
	v_cvt_pk_bf16_f32 v11, v180, v181
	v_cvt_pk_bf16_f32 v12, v182, v183
	v_cvt_pk_bf16_f32 v13, v184, v185
	v_cvt_pk_bf16_f32 v240, v186, v187
	v_cvt_pk_bf16_f32 v241, v188, v189
	v_cvt_pk_bf16_f32 v242, v190, v191
	v_cvt_pk_bf16_f32 v243, v192, v193
	s_waitcnt lgkmcnt(0)
	s_nop 0
	v_mfma_f32_32x32x16_bf16 v[48:63], v[232:235], v[10:13], v[48:63]
	v_add_f32_e32 v194, v178, v179
	v_add_f32_e32 v195, v180, v181
	v_add_f32_e32 v155, v182, v183
	v_add_f32_e32 v169, v184, v185
	v_add_f32_e32 v194, v186, v194
	v_mfma_f32_32x32x16_bf16 v[48:63], v[236:239], v[240:243], v[48:63]
	v_add_f32_e32 v195, v187, v195
	v_add_f32_e32 v155, v188, v155
	v_add_f32_e32 v169, v189, v169
	v_add_f32_e32 v194, v190, v194
	v_add_f32_e32 v195, v191, v195
	v_mfma_f32_32x32x16_bf16 v[64:79], v[244:247], v[10:13], v[64:79]
	v_add_f32_e32 v155, v192, v155
	v_add_f32_e32 v169, v193, v169
	v_add_f32_e32 v194, v194, v195
	v_add_f32_e32 v155, v155, v169
	v_add_f32_e32 v194, v194, v155
	v_mfma_f32_32x32x16_bf16 v[64:79], v[214:217], v[240:243], v[64:79]
	v_fmac_f32_e32 v194, v151, v0
	v_mov_b32_e32 v151, v194
	ds_read_b128 v[2:5], v164 offset:7680
	ds_read_b128 v[6:9], v164 offset:7712
	ds_read2_b64 v[232:235], v129 offset0:16 offset1:18
	ds_read2_b64 v[236:239], v129 offset0:20 offset1:22
	ds_read2_b64 v[244:247], v173 offset0:48 offset1:50
	ds_read2_b64 v[214:217], v173 offset0:52 offset1:54
	s_waitcnt lgkmcnt(4)
	v_mfma_f32_32x32x16_bf16 v[178:193], v[2:5], v[96:99], 0
	v_mfma_f32_32x32x16_bf16 v[178:193], v[6:9], v[100:103], v[178:193]
	v_max3_f32 v248, v80, v81, v82
	v_max3_f32 v249, v83, v84, v85
	v_max3_f32 v218, v86, v87, v88
	v_max3_f32 v219, v89, v90, v91
	v_max3_f32 v220, v92, v93, v94
	v_max3_f32 v248, v248, v249, v218
	v_max3_f32 v219, v219, v220, v95
	v_max_f32_e32 v248, v248, v219
	v_mov_b32_e32 v249, v248
	s_nop 1
	v_permlane32_swap_b32_e32 v248, v249
	v_max_f32_e32 v248, v248, v249
	v_mul_f32_e32 v248, 0x3e8293ee, v248
	v_max_f32_e32 v218, v133, v248
	v_sub_f32_e32 v0, v133, v218
	v_exp_f32_e32 v0, v0
	v_mov_b32_e32 v133, v218
	v_cmp_neq_f32_e32 vcc, 1.0, v0
	s_cmp_lg_u64 vcc, 0
	s_cbranch_scc0 .Lattn1_norescale_2
	v_pk_mul_f32 v[48:49], v[48:49], v[0:1] op_sel_hi:[1,0]
	v_pk_mul_f32 v[50:51], v[50:51], v[0:1] op_sel_hi:[1,0]
	v_pk_mul_f32 v[52:53], v[52:53], v[0:1] op_sel_hi:[1,0]
	v_pk_mul_f32 v[54:55], v[54:55], v[0:1] op_sel_hi:[1,0]
	v_pk_mul_f32 v[56:57], v[56:57], v[0:1] op_sel_hi:[1,0]
	v_pk_mul_f32 v[58:59], v[58:59], v[0:1] op_sel_hi:[1,0]
	v_pk_mul_f32 v[60:61], v[60:61], v[0:1] op_sel_hi:[1,0]
	v_pk_mul_f32 v[62:63], v[62:63], v[0:1] op_sel_hi:[1,0]
	v_pk_mul_f32 v[64:65], v[64:65], v[0:1] op_sel_hi:[1,0]
	v_pk_mul_f32 v[66:67], v[66:67], v[0:1] op_sel_hi:[1,0]
	v_pk_mul_f32 v[68:69], v[68:69], v[0:1] op_sel_hi:[1,0]
	v_pk_mul_f32 v[70:71], v[70:71], v[0:1] op_sel_hi:[1,0]
	v_pk_mul_f32 v[72:73], v[72:73], v[0:1] op_sel_hi:[1,0]
	v_pk_mul_f32 v[74:75], v[74:75], v[0:1] op_sel_hi:[1,0]
	v_pk_mul_f32 v[76:77], v[76:77], v[0:1] op_sel_hi:[1,0]
	v_pk_mul_f32 v[78:79], v[78:79], v[0:1] op_sel_hi:[1,0]
.Lattn1_norescale_2:
	v_fma_f32 v15, v80, s39, -v133
	v_exp_f32_e32 v80, v15
	v_fma_f32 v153, v81, s39, -v133
	v_exp_f32_e32 v81, v153
	v_fma_f32 v15, v82, s39, -v133
	v_exp_f32_e32 v82, v15
	v_fma_f32 v153, v83, s39, -v133
	v_exp_f32_e32 v83, v153
	v_fma_f32 v15, v84, s39, -v133
	v_exp_f32_e32 v84, v15
	v_fma_f32 v153, v85, s39, -v133
	v_exp_f32_e32 v85, v153
	v_fma_f32 v15, v86, s39, -v133
	v_exp_f32_e32 v86, v15
	v_fma_f32 v153, v87, s39, -v133
	v_exp_f32_e32 v87, v153
	v_fma_f32 v15, v88, s39, -v133
	v_exp_f32_e32 v88, v15
	v_fma_f32 v153, v89, s39, -v133
	v_exp_f32_e32 v89, v153
	v_fma_f32 v15, v90, s39, -v133
	v_exp_f32_e32 v90, v15
	v_fma_f32 v153, v91, s39, -v133
	v_exp_f32_e32 v91, v153
	v_fma_f32 v15, v92, s39, -v133
	v_exp_f32_e32 v92, v15
	v_fma_f32 v153, v93, s39, -v133
	v_exp_f32_e32 v93, v153
	v_fma_f32 v15, v94, s39, -v133
	v_exp_f32_e32 v94, v15
	v_fma_f32 v153, v95, s39, -v133
	v_exp_f32_e32 v95, v153
	v_cvt_pk_bf16_f32 v10, v80, v81
	v_cvt_pk_bf16_f32 v11, v82, v83
	v_cvt_pk_bf16_f32 v12, v84, v85
	v_cvt_pk_bf16_f32 v13, v86, v87
	v_cvt_pk_bf16_f32 v240, v88, v89
	v_cvt_pk_bf16_f32 v241, v90, v91
	v_cvt_pk_bf16_f32 v242, v92, v93
	v_cvt_pk_bf16_f32 v243, v94, v95
	s_waitcnt lgkmcnt(0)
	s_nop 0
	v_mfma_f32_32x32x16_bf16 v[48:63], v[232:235], v[10:13], v[48:63]
	v_add_f32_e32 v194, v80, v81
	v_add_f32_e32 v195, v82, v83
	v_add_f32_e32 v155, v84, v85
	v_add_f32_e32 v169, v86, v87
	v_add_f32_e32 v194, v88, v194
	v_mfma_f32_32x32x16_bf16 v[48:63], v[236:239], v[240:243], v[48:63]
	v_add_f32_e32 v195, v89, v195
	v_add_f32_e32 v155, v90, v155
	v_add_f32_e32 v169, v91, v169
	v_add_f32_e32 v194, v92, v194
	v_add_f32_e32 v195, v93, v195
	v_mfma_f32_32x32x16_bf16 v[64:79], v[244:247], v[10:13], v[64:79]
	v_add_f32_e32 v155, v94, v155
	v_add_f32_e32 v169, v95, v169
	v_add_f32_e32 v194, v194, v195
	v_add_f32_e32 v155, v155, v169
	v_add_f32_e32 v194, v194, v155
	v_mfma_f32_32x32x16_bf16 v[64:79], v[214:217], v[240:243], v[64:79]
	v_fmac_f32_e32 v194, v151, v0
	v_mov_b32_e32 v151, v194
	ds_read2_b64 v[232:235], v129 offset0:24 offset1:26
	ds_read2_b64 v[236:239], v129 offset0:28 offset1:30
	ds_read2_b64 v[244:247], v173 offset0:56 offset1:58
	ds_read2_b64 v[214:217], v173 offset0:60 offset1:62
	v_max3_f32 v248, v178, v179, v180
	v_max3_f32 v249, v181, v182, v183
	v_max3_f32 v218, v184, v185, v186
	v_max3_f32 v219, v187, v188, v189
	v_max3_f32 v220, v190, v191, v192
	v_max3_f32 v248, v248, v249, v218
	v_max3_f32 v219, v219, v220, v193
	v_max_f32_e32 v248, v248, v219
	v_mov_b32_e32 v249, v248
	s_nop 1
	v_permlane32_swap_b32_e32 v248, v249
	v_max_f32_e32 v248, v248, v249
	v_mul_f32_e32 v248, 0x3e8293ee, v248
	v_max_f32_e32 v218, v133, v248
	v_sub_f32_e32 v0, v133, v218
	v_exp_f32_e32 v0, v0
	v_mov_b32_e32 v133, v218
	v_cmp_neq_f32_e32 vcc, 1.0, v0
	s_cmp_lg_u64 vcc, 0
	s_cbranch_scc0 .Lattn1_norescale_3
	v_pk_mul_f32 v[48:49], v[48:49], v[0:1] op_sel_hi:[1,0]
	v_pk_mul_f32 v[50:51], v[50:51], v[0:1] op_sel_hi:[1,0]
	v_pk_mul_f32 v[52:53], v[52:53], v[0:1] op_sel_hi:[1,0]
	v_pk_mul_f32 v[54:55], v[54:55], v[0:1] op_sel_hi:[1,0]
	v_pk_mul_f32 v[56:57], v[56:57], v[0:1] op_sel_hi:[1,0]
	v_pk_mul_f32 v[58:59], v[58:59], v[0:1] op_sel_hi:[1,0]
	v_pk_mul_f32 v[60:61], v[60:61], v[0:1] op_sel_hi:[1,0]
	v_pk_mul_f32 v[62:63], v[62:63], v[0:1] op_sel_hi:[1,0]
	v_pk_mul_f32 v[64:65], v[64:65], v[0:1] op_sel_hi:[1,0]
	v_pk_mul_f32 v[66:67], v[66:67], v[0:1] op_sel_hi:[1,0]
	v_pk_mul_f32 v[68:69], v[68:69], v[0:1] op_sel_hi:[1,0]
	v_pk_mul_f32 v[70:71], v[70:71], v[0:1] op_sel_hi:[1,0]
	v_pk_mul_f32 v[72:73], v[72:73], v[0:1] op_sel_hi:[1,0]
	v_pk_mul_f32 v[74:75], v[74:75], v[0:1] op_sel_hi:[1,0]
	v_pk_mul_f32 v[76:77], v[76:77], v[0:1] op_sel_hi:[1,0]
	v_pk_mul_f32 v[78:79], v[78:79], v[0:1] op_sel_hi:[1,0]
.Lattn1_norescale_3:
	v_fma_f32 v15, v178, s39, -v133
	v_exp_f32_e32 v178, v15
	v_fma_f32 v153, v179, s39, -v133
	v_exp_f32_e32 v179, v153
	v_fma_f32 v15, v180, s39, -v133
	v_exp_f32_e32 v180, v15
	v_fma_f32 v153, v181, s39, -v133
	v_exp_f32_e32 v181, v153
	v_fma_f32 v15, v182, s39, -v133
	v_exp_f32_e32 v182, v15
	v_fma_f32 v153, v183, s39, -v133
	v_exp_f32_e32 v183, v153
	v_fma_f32 v15, v184, s39, -v133
	v_exp_f32_e32 v184, v15
	v_fma_f32 v153, v185, s39, -v133
	v_exp_f32_e32 v185, v153
	v_fma_f32 v15, v186, s39, -v133
	v_exp_f32_e32 v186, v15
	v_fma_f32 v153, v187, s39, -v133
	v_exp_f32_e32 v187, v153
	v_fma_f32 v15, v188, s39, -v133
	v_exp_f32_e32 v188, v15
	v_fma_f32 v153, v189, s39, -v133
	v_exp_f32_e32 v189, v153
	v_fma_f32 v15, v190, s39, -v133
	v_exp_f32_e32 v190, v15
	v_fma_f32 v153, v191, s39, -v133
	v_exp_f32_e32 v191, v153
	v_fma_f32 v15, v192, s39, -v133
	v_exp_f32_e32 v192, v15
	v_fma_f32 v153, v193, s39, -v133
	v_exp_f32_e32 v193, v153
	v_cvt_pk_bf16_f32 v10, v178, v179
	v_cvt_pk_bf16_f32 v11, v180, v181
	v_cvt_pk_bf16_f32 v12, v182, v183
	v_cvt_pk_bf16_f32 v13, v184, v185
	v_cvt_pk_bf16_f32 v240, v186, v187
	v_cvt_pk_bf16_f32 v241, v188, v189
	v_cvt_pk_bf16_f32 v242, v190, v191
	v_cvt_pk_bf16_f32 v243, v192, v193
	s_waitcnt lgkmcnt(0)
	s_nop 0
	v_mfma_f32_32x32x16_bf16 v[48:63], v[232:235], v[10:13], v[48:63]
	v_add_f32_e32 v194, v178, v179
	v_add_f32_e32 v195, v180, v181
	v_add_f32_e32 v155, v182, v183
	v_add_f32_e32 v169, v184, v185
	v_add_f32_e32 v194, v186, v194
	v_mfma_f32_32x32x16_bf16 v[48:63], v[236:239], v[240:243], v[48:63]
	v_add_f32_e32 v195, v187, v195
	v_add_f32_e32 v155, v188, v155
	v_add_f32_e32 v169, v189, v169
	v_add_f32_e32 v194, v190, v194
	v_add_f32_e32 v195, v191, v195
	v_mfma_f32_32x32x16_bf16 v[64:79], v[244:247], v[10:13], v[64:79]
	v_add_f32_e32 v155, v192, v155
	v_add_f32_e32 v169, v193, v169
	v_add_f32_e32 v194, v194, v195
	v_add_f32_e32 v155, v155, v169
	v_add_f32_e32 v194, v194, v155
	v_mfma_f32_32x32x16_bf16 v[64:79], v[214:217], v[240:243], v[64:79]
	v_fmac_f32_e32 v194, v151, v0
	v_mov_b32_e32 v2, v194

.LBB0_561:
	s_add_i32 s90, s30, 1
	s_cmp_lg_u32 s30, 15
	s_cselect_b64 s[28:29], -1, 0
	s_mov_b32 s94, 0
	s_mov_b32 s95, 0
	s_cmp_gt_u32 s33, 0x10000
	s_cbranch_scc1 .Lsc1_vb1_top
	s_cmp_eq_u32 s30, 15
	s_cbranch_scc1 .LBB0_595
.Lsc1_L:
	v_lshl_or_b32 v0, s90, 4, v74
	v_sub_u32_e32 v18, 0xff, v0
	v_cndmask_b32_e64 v19, v18, v0, s[40:41]
	v_add_u32_e32 v18, s53, v19
	s_movk_i32 s0, 0x1c00
	s_waitcnt lgkmcnt(5)
	v_mad_i64_i32 v[20:21], s[0:1], v18, s0, v[58:59]
	v_add_co_u32_e32 v22, vcc, 0x1000, v20
	v_cmp_lt_i32_e64 s[46:47], 0, v19
	s_waitcnt lgkmcnt(4)
	v_addc_co_u32_e32 v23, vcc, 0, v21, vcc
	global_load_dword v84, v[20:21], off
	global_load_dword v85, v[20:21], off offset:2048
	global_load_dword v86, v[22:23], off
	s_waitcnt vmcnt(20)
	v_mov_b32_e32 v87, 0
	v_mov_b32_e32 v88, 0
	v_mov_b32_e32 v89, 0
	s_and_saveexec_b64 s[0:1], s[46:47]
	s_cbranch_execz .LBB0_564
	v_add_co_u32_e32 v22, vcc, 0xfffff000, v20
	s_nop 1
	v_addc_co_u32_e32 v23, vcc, -1, v21, vcc
	global_load_dword v88, v[22:23], off offset:-3072
	global_load_dword v89, v[22:23], off offset:-1024

.LBB0_595:
	s_cmp_eq_u32 s95, 1
	s_cbranch_scc0 .Lsc1_j0
	s_mov_b32 s95, 0
	s_waitcnt vmcnt(0)
	s_branch .LBB0_601
.Lsc1_j0:
	s_sub_i32 s90, s90, s94
	s_mov_b32 s94, 0
	s_bitcmp1_b32 s30, 0
	s_cselect_b32 s46, 0x6080, 0
	s_add_i32 s0, s33, s46
	v_lshl_add_u32 v140, v136, 2, s0
	v_add_u32_e32 v141, s46, v138
	s_add_i32 s0, s50, s46
	v_mov_b32_e32 v231, s0
	s_add_i32 s0, s88, -1
	s_add_i32 s1, s89, 1
	s_movk_i32 s91, 0x800
	s_movk_i32 s92, 0xf800
	s_and_b64 vcc, s[40:41], exec
	s_cselect_b32 s30, s0, s1
	s_cselect_b32 s91, s91, s92
	s_add_i32 s30, s30, s53
	s_lshl_b32 s30, s30, 11
	s_movk_i32 s47, 8
	s_waitcnt lgkmcnt(0)
	ds_read_b128 v[18:21], v140 offset:4096
	ds_read_b128 v[22:25], v140 offset:4112
	ds_read_b128 v[26:29], v140 offset:16384
	ds_read_b128 v[30:33], v140 offset:16400
	ds_read_b64 v[66:67], v141
	ds_read2_b32 v[68:69], v231 offset0:0 offset1:16
	ds_read_b128 v[42:45], v140 offset:8192
	ds_read_b128 v[46:49], v140 offset:8208
	ds_read_b128 v[34:37], v140
	ds_read_b128 v[38:41], v140 offset:16
	ds_read_b128 v[50:53], v140 offset:12288
	ds_read_b128 v[54:57], v140 offset:12304
.Lscan1_loop:
	s_waitcnt lgkmcnt(0)
	ds_read_b128 v[162:165], v140 offset:4352
	ds_read_b128 v[166:169], v140 offset:4368
	ds_read_b128 v[170:173], v140 offset:16640
	ds_read_b128 v[174:177], v140 offset:16656
	ds_read_b64 v[240:241], v141 offset:256
	ds_read2_b32 v[242:243], v231 offset0:1 offset1:17
	ds_read_b128 v[186:189], v140 offset:8448
	ds_read_b128 v[190:193], v140 offset:8464
	ds_read_b128 v[178:181], v140 offset:256
	ds_read_b128 v[182:185], v140 offset:272
	ds_read_b128 v[232:235], v140 offset:12544
	ds_read_b128 v[236:239], v140 offset:12560
	v_pk_mul_f32 v[142:143], v[18:19], v[14:15]
	v_pk_mul_f32 v[144:145], v[18:19], v[6:7]
	v_pk_mul_f32 v[244:245], v[26:27], v[14:15]
	v_pk_mul_f32 v[246:247], v[26:27], v[6:7]
	v_pk_fma_f32 v[142:143], v[20:21], v[16:17], v[142:143]
	v_pk_fma_f32 v[144:145], v[20:21], v[8:9], v[144:145]
	v_pk_fma_f32 v[244:245], v[28:29], v[16:17], v[244:245]
	v_pk_fma_f32 v[246:247], v[28:29], v[8:9], v[246:247]
	v_pk_fma_f32 v[142:143], v[22:23], v[10:11], v[142:143]
	v_pk_fma_f32 v[144:145], v[22:23], v[2:3], v[144:145]
	v_pk_fma_f32 v[244:245], v[30:31], v[10:11], v[244:245]
	v_pk_fma_f32 v[246:247], v[30:31], v[2:3], v[246:247]
	v_pk_fma_f32 v[142:143], v[24:25], v[12:13], v[142:143]
	v_pk_fma_f32 v[144:145], v[24:25], v[4:5], v[144:145]
	v_pk_fma_f32 v[244:245], v[32:33], v[12:13], v[244:245]
	v_pk_fma_f32 v[246:247], v[32:33], v[4:5], v[246:247]
	v_add_f32_e32 v70, v142, v143
	v_add_f32_e32 v71, v144, v145
	v_add_f32_e32 v72, v244, v245
	v_add_f32_e32 v73, v246, v247
	v_add_f32_dpp v70, v70, v70 quad_perm:[1,0,3,2] row_mask:0xf bank_mask:0xf bound_ctrl:1
	v_add_f32_dpp v71, v71, v71 quad_perm:[1,0,3,2] row_mask:0xf bank_mask:0xf bound_ctrl:1
	v_add_f32_dpp v72, v72, v72 quad_perm:[1,0,3,2] row_mask:0xf bank_mask:0xf bound_ctrl:1
	v_add_f32_dpp v73, v73, v73 quad_perm:[1,0,3,2] row_mask:0xf bank_mask:0xf bound_ctrl:1
	v_add_f32_dpp v70, v70, v70 quad_perm:[2,3,0,1] row_mask:0xf bank_mask:0xf bound_ctrl:1
	v_add_f32_dpp v71, v71, v71 quad_perm:[2,3,0,1] row_mask:0xf bank_mask:0xf bound_ctrl:1
	v_add_f32_dpp v72, v72, v72 quad_perm:[2,3,0,1] row_mask:0xf bank_mask:0xf bound_ctrl:1
	v_add_f32_dpp v73, v73, v73 quad_perm:[2,3,0,1] row_mask:0xf bank_mask:0xf bound_ctrl:1
	v_add_f32_dpp v70, v70, v70 row_half_mirror row_mask:0xf bank_mask:0xf bound_ctrl:1
	v_add_f32_dpp v71, v71, v71 row_half_mirror row_mask:0xf bank_mask:0xf bound_ctrl:1
	v_add_f32_dpp v72, v72, v72 row_half_mirror row_mask:0xf bank_mask:0xf bound_ctrl:1
	v_add_f32_dpp v73, v73, v73 row_half_mirror row_mask:0xf bank_mask:0xf bound_ctrl:1
	v_pk_fma_f32 v[72:73], v[70:71], v[68:69], v[72:73] op_sel_hi:[1,0,1]
	v_pk_fma_f32 v[72:73], v[66:67], v[68:69], v[72:73] op_sel:[0,1,0]
	v_lshl_add_u64 v[248:249], v[64:65], 0, s[30:31]
	s_and_saveexec_b64 s[0:1], s[44:45]
	global_store_dwordx2 v[248:249], v[72:73], off
	s_mov_b64 exec, s[0:1]
	s_add_i32 s30, s30, s91
	v_pk_mul_f32 v[142:143], v[70:71], v[42:43] op_sel_hi:[0,1]
	v_pk_mul_f32 v[144:145], v[70:71], v[42:43] op_sel:[1,0]
	v_pk_fma_f32 v[14:15], v[14:15], v[34:35], v[142:143]
	v_pk_fma_f32 v[6:7], v[6:7], v[34:35], v[144:145]
	v_pk_fma_f32 v[14:15], v[66:67], v[50:51], v[14:15] op_sel_hi:[0,1,1]
	v_pk_fma_f32 v[6:7], v[66:67], v[50:51], v[6:7] op_sel:[1,0,0]
	v_pk_mul_f32 v[244:245], v[70:71], v[44:45] op_sel_hi:[0,1]
	v_pk_mul_f32 v[246:247], v[70:71], v[44:45] op_sel:[1,0]
	v_pk_fma_f32 v[16:17], v[16:17], v[36:37], v[244:245]
	v_pk_fma_f32 v[8:9], v[8:9], v[36:37], v[246:247]
	v_pk_fma_f32 v[16:17], v[66:67], v[52:53], v[16:17] op_sel_hi:[0,1,1]
	v_pk_fma_f32 v[8:9], v[66:67], v[52:53], v[8:9] op_sel:[1,0,0]
	v_pk_mul_f32 v[142:143], v[70:71], v[46:47] op_sel_hi:[0,1]
	v_pk_mul_f32 v[144:145], v[70:71], v[46:47] op_sel:[1,0]
	v_pk_fma_f32 v[10:11], v[10:11], v[38:39], v[142:143]
	v_pk_fma_f32 v[2:3], v[2:3], v[38:39], v[144:145]
	v_pk_fma_f32 v[10:11], v[66:67], v[54:55], v[10:11] op_sel_hi:[0,1,1]
	v_pk_fma_f32 v[2:3], v[66:67], v[54:55], v[2:3] op_sel:[1,0,0]
	v_pk_mul_f32 v[244:245], v[70:71], v[48:49] op_sel_hi:[0,1]
	v_pk_mul_f32 v[246:247], v[70:71], v[48:49] op_sel:[1,0]
	v_pk_fma_f32 v[12:13], v[12:13], v[40:41], v[244:245]
	v_pk_fma_f32 v[4:5], v[4:5], v[40:41], v[246:247]
	v_pk_fma_f32 v[12:13], v[66:67], v[56:57], v[12:13] op_sel_hi:[0,1,1]
	v_pk_fma_f32 v[4:5], v[66:67], v[56:57], v[4:5] op_sel:[1,0,0]
	s_waitcnt lgkmcnt(0)
	ds_read_b128 v[18:21], v140 offset:4608
	ds_read_b128 v[22:25], v140 offset:4624
	ds_read_b128 v[26:29], v140 offset:16896
	ds_read_b128 v[30:33], v140 offset:16912
	ds_read_b64 v[66:67], v141 offset:512
	ds_read2_b32 v[68:69], v231 offset0:2 offset1:18
	ds_read_b128 v[42:45], v140 offset:8704
	ds_read_b128 v[46:49], v140 offset:8720
	ds_read_b128 v[34:37], v140 offset:512
	ds_read_b128 v[38:41], v140 offset:528
	ds_read_b128 v[50:53], v140 offset:12800
	ds_read_b128 v[54:57], v140 offset:12816
	v_pk_mul_f32 v[142:143], v[162:163], v[14:15]
	v_pk_mul_f32 v[144:145], v[162:163], v[6:7]
	v_pk_mul_f32 v[244:245], v[170:171], v[14:15]
	v_pk_mul_f32 v[246:247], v[170:171], v[6:7]
	v_pk_fma_f32 v[142:143], v[164:165], v[16:17], v[142:143]
	v_pk_fma_f32 v[144:145], v[164:165], v[8:9], v[144:145]
	v_pk_fma_f32 v[244:245], v[172:173], v[16:17], v[244:245]
	v_pk_fma_f32 v[246:247], v[172:173], v[8:9], v[246:247]
	v_pk_fma_f32 v[142:143], v[166:167], v[10:11], v[142:143]
	v_pk_fma_f32 v[144:145], v[166:167], v[2:3], v[144:145]
	v_pk_fma_f32 v[244:245], v[174:175], v[10:11], v[244:245]
	v_pk_fma_f32 v[246:247], v[174:175], v[2:3], v[246:247]
	v_pk_fma_f32 v[142:143], v[168:169], v[12:13], v[142:143]
	v_pk_fma_f32 v[144:145], v[168:169], v[4:5], v[144:145]
	v_pk_fma_f32 v[244:245], v[176:177], v[12:13], v[244:245]
	v_pk_fma_f32 v[246:247], v[176:177], v[4:5], v[246:247]
	v_add_f32_e32 v70, v142, v143
	v_add_f32_e32 v71, v144, v145
	v_add_f32_e32 v72, v244, v245
	v_add_f32_e32 v73, v246, v247
	v_add_f32_dpp v70, v70, v70 quad_perm:[1,0,3,2] row_mask:0xf bank_mask:0xf bound_ctrl:1
	v_add_f32_dpp v71, v71, v71 quad_perm:[1,0,3,2] row_mask:0xf bank_mask:0xf bound_ctrl:1
	v_add_f32_dpp v72, v72, v72 quad_perm:[1,0,3,2] row_mask:0xf bank_mask:0xf bound_ctrl:1
	v_add_f32_dpp v73, v73, v73 quad_perm:[1,0,3,2] row_mask:0xf bank_mask:0xf bound_ctrl:1
	v_add_f32_dpp v70, v70, v70 quad_perm:[2,3,0,1] row_mask:0xf bank_mask:0xf bound_ctrl:1
	v_add_f32_dpp v71, v71, v71 quad_perm:[2,3,0,1] row_mask:0xf bank_mask:0xf bound_ctrl:1
	v_add_f32_dpp v72, v72, v72 quad_perm:[2,3,0,1] row_mask:0xf bank_mask:0xf bound_ctrl:1
	v_add_f32_dpp v73, v73, v73 quad_perm:[2,3,0,1] row_mask:0xf bank_mask:0xf bound_ctrl:1
	v_add_f32_dpp v70, v70, v70 row_half_mirror row_mask:0xf bank_mask:0xf bound_ctrl:1
	v_add_f32_dpp v71, v71, v71 row_half_mirror row_mask:0xf bank_mask:0xf bound_ctrl:1
	v_add_f32_dpp v72, v72, v72 row_half_mirror row_mask:0xf bank_mask:0xf bound_ctrl:1
	v_add_f32_dpp v73, v73, v73 row_half_mirror row_mask:0xf bank_mask:0xf bound_ctrl:1
	v_pk_fma_f32 v[72:73], v[70:71], v[242:243], v[72:73] op_sel_hi:[1,0,1]
	v_pk_fma_f32 v[72:73], v[240:241], v[242:243], v[72:73] op_sel:[0,1,0]
	v_lshl_add_u64 v[248:249], v[64:65], 0, s[30:31]
	s_and_saveexec_b64 s[0:1], s[44:45]
	global_store_dwordx2 v[248:249], v[72:73], off
	s_mov_b64 exec, s[0:1]
	s_add_i32 s30, s30, s91
	v_pk_mul_f32 v[142:143], v[70:71], v[186:187] op_sel_hi:[0,1]
	v_pk_mul_f32 v[144:145], v[70:71], v[186:187] op_sel:[1,0]
	v_pk_fma_f32 v[14:15], v[14:15], v[178:179], v[142:143]
	v_pk_fma_f32 v[6:7], v[6:7], v[178:179], v[144:145]
	v_pk_fma_f32 v[14:15], v[240:241], v[232:233], v[14:15] op_sel_hi:[0,1,1]
	v_pk_fma_f32 v[6:7], v[240:241], v[232:233], v[6:7] op_sel:[1,0,0]
	v_pk_mul_f32 v[244:245], v[70:71], v[188:189] op_sel_hi:[0,1]
	v_pk_mul_f32 v[246:247], v[70:71], v[188:189] op_sel:[1,0]
	v_pk_fma_f32 v[16:17], v[16:17], v[180:181], v[244:245]
	v_pk_fma_f32 v[8:9], v[8:9], v[180:181], v[246:247]
	v_pk_fma_f32 v[16:17], v[240:241], v[234:235], v[16:17] op_sel_hi:[0,1,1]
	v_pk_fma_f32 v[8:9], v[240:241], v[234:235], v[8:9] op_sel:[1,0,0]
	v_pk_mul_f32 v[142:143], v[70:71], v[190:191] op_sel_hi:[0,1]
	v_pk_mul_f32 v[144:145], v[70:71], v[190:191] op_sel:[1,0]
	v_pk_fma_f32 v[10:11], v[10:11], v[182:183], v[142:143]
	v_pk_fma_f32 v[2:3], v[2:3], v[182:183], v[144:145]
	v_pk_fma_f32 v[10:11], v[240:241], v[236:237], v[10:11] op_sel_hi:[0,1,1]
	v_pk_fma_f32 v[2:3], v[240:241], v[236:237], v[2:3] op_sel:[1,0,0]
	v_pk_mul_f32 v[244:245], v[70:71], v[192:193] op_sel_hi:[0,1]
	v_pk_mul_f32 v[246:247], v[70:71], v[192:193] op_sel:[1,0]
	v_pk_fma_f32 v[12:13], v[12:13], v[184:185], v[244:245]
	v_pk_fma_f32 v[4:5], v[4:5], v[184:185], v[246:247]
	v_pk_fma_f32 v[12:13], v[240:241], v[238:239], v[12:13] op_sel_hi:[0,1,1]
	v_pk_fma_f32 v[4:5], v[240:241], v[238:239], v[4:5] op_sel:[1,0,0]
	v_add_u32_e32 v140, 0x200, v140
	v_add_u32_e32 v141, 0x200, v141
	v_add_u32_e32 v231, 8, v231
	s_add_i32 s47, s47, -1
	s_cmp_lg_u32 s47, 0
	s_cbranch_scc1 .Lscan1_loop
	s_cmp_gt_u32 s33, 0x10000
	s_cbranch_scc1 .Lsc1_barrier

.LBB0_611:
	s_cmp_gt_u32 s33, 0x10000
	s_cbranch_scc1 .Lsc1_vb1_afterF

.Lsc1_vb1_top:
	s_cmp_lg_u32 s30, 0
	s_cbranch_scc1 .LBB0_601
	s_mov_b32 s95, 1
	s_branch .Lsc1_L
.Lsc1_vb1_afterF:
	s_cmp_gt_u32 s30, 13
	s_cbranch_scc1 .LBB0_595
	s_add_i32 s90, s90, 1
	s_mov_b32 s94, 1
	s_branch .Lsc1_L
